# v60 plus retention output phase: four 8-byte row stores per item widened to two 16-byte stores via v_permlane32_swap pairs
# baseline (speedup 1.0000x reference)
; __device__ __forceinline__ unsigned cvtpk(float lo, float hi) { f32x2_t v = {lo, hi}; bf16x2_t b = __builtin_convertvector(v, bf16x2_t); return __builtin_bit_cast(unsigned, b); }
; __device__ __forceinline__ void wait_all_barrier() { asm volatile("s_waitcnt vmcnt(0) lgkmcnt(0)\n\ts_barrier" ::: "memory"); }
; __device__ __forceinline__ void r3_phase(ldsp lds, const bf16* U, const bf16* PREV, bf16* O, const float* gnw, int G, int bx, int wave, int lane) {
;     ...
;         if (hh == 0) red[(et * 2 + it) * 32 + r] = ssq;
;         wait_all_barrier();
;         const float tot = (red[(0 * 2 + it) * 32 + r] + red[(1 * 2 + it) * 32 + r]) + (red[(2 * 2 + it) * 32 + r] + red[(3 * 2 + it) * 32 + r]);
;         const float rs = 1.0f / sqrtf(tot * (1.0f / 128.0f) + EPS);
;         const size_t tok = (size_t)b * SEQ + 64 * n + irow;
;         const float* gb = gnw; asm volatile("" : "+s"(gb));
;         const float* gp = gb + h * 128 + 32 * et + 4 * hh;
;         const bf16* gatep = U + tok * INW + 1536 + h * 128 + 32 * et + 4 * hh;
;         bf16* op = O + tok * D + h * 128 + 32 * et + 4 * hh;
;         f32x4 wq4[4]; v2u gq4[4];
; #pragma unroll
;         for (int g4 = 0; g4 < 4; ++g4) { wq4[g4] = *(const f32x4*)(gp + 8 * g4); gq4[g4] = *(const v2u*)(gatep + 8 * g4); }
; #pragma unroll
;         for (int g4 = 0; g4 < 4; ++g4) { const f32x4 w = wq4[g4]; const v2u gt = gq4[g4];
;             v2u pk; pk.x = cvtpk(oin[4 * g4] * rs * w[0] * bflo(gt.x), oin[4 * g4 + 1] * rs * w[1] * bfhi(gt.x));
;             pk.y = cvtpk(oin[4 * g4 + 2] * rs * w[2] * bflo(gt.y), oin[4 * g4 + 3] * rs * w[3] * bfhi(gt.y));
;             *(v2u*)(op + 8 * g4) = pk; }
.LBB0_360:
	s_or_b64 exec, exec, s[14:15]
	s_waitcnt vmcnt(0) lgkmcnt(0)
	s_barrier
	v_lshl_add_u32 v8, v60, 2, s37
	s_add_i32 s15, s37, s31
	ds_read_b32 v28, v8
	v_lshl_add_u32 v8, v59, 2, s15
	s_ashr_i32 s14, s26, 6
	ds_read2st64_b32 v[30:31], v8 offset0:1 offset1:2
	v_lshl_add_u32 v8, v71, 2, s37
	s_lshl_b32 s37, s26, 6
	s_mulk_i32 s26, 0xfd00
	s_ashr_i32 s15, s14, 31
	s_add_i32 s52, s41, s26
	s_lshl_b64 s[14:15], s[14:15], 12
	s_and_b32 s37, s37, 0xfc0
	s_ashr_i32 s53, s52, 31
	s_or_b32 s14, s14, s37
	s_mov_b64 s[50:51], s[18:19]
	s_lshl_b64 s[54:55], s[52:53], 2
	ds_read_b32 v46, v8
	v_or_b32_e32 v24, s14, v60
	s_add_u32 s14, s50, s54
	s_addc_u32 s26, s51, s55
	s_lshl_b32 s37, s33, 2
	s_add_u32 s50, s14, s37
	s_addc_u32 s51, s26, 0
	v_lshlrev_b32_e32 v50, 2, v62
	s_waitcnt lgkmcnt(3)
	v_mov_b64_e32 v[8:9], s[22:23]
	v_lshl_add_u64 v[26:27], s[50:51], 0, v[50:51]
	v_mad_u64_u32 v[8:9], s[50:51], v24, s40, v[8:9]
	v_mad_i32_i24 v9, s15, v127, v9
	s_lshl_b64 s[50:51], s[52:53], 1
	v_lshl_add_u64 v[8:9], v[8:9], 0, s[50:51]
	s_lshl_b32 s26, s33, 1
	v_lshl_add_u64 v[8:9], v[8:9], 0, s[26:27]
	v_lshlrev_b32_e32 v50, 1, v62
	v_lshl_add_u64 v[36:37], v[8:9], 0, v[50:51]
	s_nop 0
	s_nop 0
	s_nop 0
	s_nop 0
	s_nop 0
	s_nop 0
	v_mov_b32_e32 v25, s15
	v_lshlrev_b64 v[44:45], 11, v[24:25]
	s_nop 0
	s_nop 0
	s_nop 0
	s_waitcnt lgkmcnt(0)
	v_mov_b32_e32 v29, v31
	v_mov_b32_e32 v31, v46
	v_pk_add_f32 v[28:29], v[28:29], v[30:31]
	s_add_i32 s48, s48, 1
	v_add_f32_e32 v28, v28, v29
	v_fmamk_f32 v28, v28, 0x3c000000, v125
	v_mul_f32_e32 v29, 0x4f800000, v28
	v_cmp_gt_f32_e32 vcc, s47, v28
	s_add_i32 s41, s41, s42
	s_add_i32 s43, s43, s44
	v_cndmask_b32_e32 v30, v28, v29, vcc
	v_sqrt_f32_e32 v31, v30
	v_lshl_add_u64 v[28:29], s[24:25], 0, v[44:45]
	v_lshl_add_u64 v[28:29], v[28:29], 0, s[50:51]
	v_lshl_add_u64 v[28:29], v[28:29], 0, s[26:27]
	v_add_u32_e32 v44, -1, v31
	v_add_u32_e32 v45, 1, v31
	v_fma_f32 v46, -v44, v31, v30
	v_fma_f32 v47, -v45, v31, v30
	v_cmp_ge_f32_e64 s[14:15], 0, v46
	v_lshl_add_u64 v[28:29], v[28:29], 0, v[50:51]
	v_lshl_add_u64 v[28:29], v[28:29], 0, v[50:51]
	s_nop 0
	v_cndmask_b32_e64 v31, v31, v44, s[14:15]
	v_cmp_lt_f32_e64 s[14:15], 0, v47
	s_nop 1
	v_cndmask_b32_e64 v31, v31, v45, s[14:15]
	v_mul_f32_e32 v44, 0x37800000, v31
	v_cndmask_b32_e32 v31, v31, v44, vcc
	v_cmp_class_f32_e32 vcc, v30, v126
	s_nop 1
	v_cndmask_b32_e32 v30, v31, v30, vcc
	v_div_scale_f32 v31, s[14:15], v30, v30, 1.0
	v_rcp_f32_e32 v44, v31
	v_div_scale_f32 v45, vcc, 1.0, v30, 1.0
	s_mov_b32 s15, s36
	v_fma_f32 v46, -v31, v44, 1.0
	v_fmac_f32_e32 v44, v46, v44
	v_mul_f32_e32 v46, v45, v44
	v_fma_f32 v47, -v31, v46, v45
	v_fmac_f32_e32 v46, v47, v44
	v_fma_f32 v31, -v31, v46, v45
	v_div_fmas_f32 v31, v31, v44, v46
	v_div_fixup_f32 v30, v31, v30, 1.0
	v_pk_mul_f32 v[34:35], v[34:35], v[30:31] op_sel_hi:[1,0]
	v_pk_mul_f32 v[32:33], v[32:33], v[30:31] op_sel_hi:[1,0]
	v_pk_mul_f32 v[6:7], v[6:7], v[30:31] op_sel_hi:[1,0]
	v_pk_mul_f32 v[4:5], v[4:5], v[30:31] op_sel_hi:[1,0]
	v_pk_mul_f32 v[2:3], v[2:3], v[30:31] op_sel_hi:[1,0]
	v_pk_mul_f32 v[0:1], v[0:1], v[30:31] op_sel_hi:[1,0]
	s_andn2_b64 vcc, exec, s[38:39]
	s_waitcnt vmcnt(0)
	v_pk_mul_f32 v[8:9], v[160:161], v[34:35]
	v_lshlrev_b32_e32 v34, 16, v176
	v_and_b32_e32 v35, 0xffff0000, v176
	v_pk_mul_f32 v[10:11], v[162:163], v[32:33]
	v_lshlrev_b32_e32 v32, 16, v177
	v_and_b32_e32 v33, 0xffff0000, v177
	v_pk_mul_f32 v[8:9], v[8:9], v[34:35]
	v_pk_mul_f32 v[10:11], v[10:11], v[32:33]
	v_cvt_pk_bf16_f32 v8, v8, v9
	v_cvt_pk_bf16_f32 v9, v10, v11
	v_pk_mul_f32 v[184:185], v[18:19], v[30:31] op_sel_hi:[1,0]
	v_lshlrev_b32_e32 v186, 16, v178
	v_pk_mul_f32 v[184:185], v[164:165], v[184:185]
	v_and_b32_e32 v187, 0xffff0000, v178
	v_pk_mul_f32 v[184:185], v[184:185], v[186:187]
	v_pk_mul_f32 v[186:187], v[16:17], v[30:31] op_sel_hi:[1,0]
	v_lshlrev_b32_e32 v188, 16, v179
	v_pk_mul_f32 v[186:187], v[166:167], v[186:187]
	v_and_b32_e32 v189, 0xffff0000, v179
	v_pk_mul_f32 v[186:187], v[186:187], v[188:189]
	v_cvt_pk_bf16_f32 v10, v184, v185
	v_cvt_pk_bf16_f32 v11, v186, v187
	s_nop 1
	v_permlane32_swap_b32_e32 v8, v10
	v_permlane32_swap_b32_e32 v9, v11
	global_store_dwordx4 v[28:29], v[8:11], off
	s_nop 1
	v_pk_mul_f32 v[6:7], v[6:7], v[168:169]
	v_lshlrev_b32_e32 v8, 16, v180
	v_and_b32_e32 v9, 0xffff0000, v180
	v_pk_mul_f32 v[6:7], v[6:7], v[8:9]
	v_pk_mul_f32 v[4:5], v[4:5], v[170:171]
	v_lshlrev_b32_e32 v8, 16, v181
	v_and_b32_e32 v9, 0xffff0000, v181
	v_pk_mul_f32 v[4:5], v[4:5], v[8:9]
	v_cvt_pk_bf16_f32 v6, v6, v7
	v_cvt_pk_bf16_f32 v7, v4, v5
	v_pk_mul_f32 v[2:3], v[2:3], v[172:173]
	v_lshlrev_b32_e32 v4, 16, v182
	v_and_b32_e32 v5, 0xffff0000, v182
	v_pk_mul_f32 v[2:3], v[2:3], v[4:5]
	v_pk_mul_f32 v[0:1], v[0:1], v[174:175]
	v_lshlrev_b32_e32 v4, 16, v183
	v_and_b32_e32 v5, 0xffff0000, v183
	v_pk_mul_f32 v[0:1], v[0:1], v[4:5]
	v_cvt_pk_bf16_f32 v2, v2, v3
	v_cvt_pk_bf16_f32 v3, v0, v1
	v_mov_b32_e32 v4, v6
	v_mov_b32_e32 v5, v7
	v_mov_b32_e32 v6, v2
	v_mov_b32_e32 v7, v3
	s_nop 1
	v_permlane32_swap_b32_e32 v4, v6
	v_permlane32_swap_b32_e32 v5, v7
	global_store_dwordx4 v[28:29], v[4:7], off offset:32
	s_nop 1
	s_cbranch_vccz .LBB0_365

; __device__ __forceinline__ unsigned cvtpk(float lo, float hi) { f32x2_t v = {lo, hi}; bf16x2_t b = __builtin_convertvector(v, bf16x2_t); return __builtin_bit_cast(unsigned, b); }
; __device__ __forceinline__ void wait_all_barrier() { asm volatile("s_waitcnt vmcnt(0) lgkmcnt(0)\n\ts_barrier" ::: "memory"); }
; __device__ __forceinline__ void r3_phase(ldsp lds, const bf16* U, const bf16* PREV, bf16* O, const float* gnw, int G, int bx, int wave, int lane) {
;     ...
;         if (hh == 0) red[(et * 2 + it) * 32 + r] = ssq;
;         wait_all_barrier();
;         const float tot = (red[(0 * 2 + it) * 32 + r] + red[(1 * 2 + it) * 32 + r]) + (red[(2 * 2 + it) * 32 + r] + red[(3 * 2 + it) * 32 + r]);
;         const float rs = 1.0f / sqrtf(tot * (1.0f / 128.0f) + EPS);
;         const size_t tok = (size_t)b * SEQ + 64 * n + irow;
;         const float* gb = gnw; asm volatile("" : "+s"(gb));
;         const float* gp = gb + h * 128 + 32 * et + 4 * hh;
;         const bf16* gatep = U + tok * INW + 1536 + h * 128 + 32 * et + 4 * hh;
;         bf16* op = O + tok * D + h * 128 + 32 * et + 4 * hh;
;         f32x4 wq4[4]; v2u gq4[4];
; #pragma unroll
;         for (int g4 = 0; g4 < 4; ++g4) { wq4[g4] = *(const f32x4*)(gp + 8 * g4); gq4[g4] = *(const v2u*)(gatep + 8 * g4); }
; #pragma unroll
;         for (int g4 = 0; g4 < 4; ++g4) { const f32x4 w = wq4[g4]; const v2u gt = gq4[g4];
;             v2u pk; pk.x = cvtpk(oin[4 * g4] * rs * w[0] * bflo(gt.x), oin[4 * g4 + 1] * rs * w[1] * bfhi(gt.x));
;             pk.y = cvtpk(oin[4 * g4 + 2] * rs * w[2] * bflo(gt.y), oin[4 * g4 + 3] * rs * w[3] * bfhi(gt.y));
;             *(v2u*)(op + 8 * g4) = pk; }
.LBB0_1428:
	s_or_b64 exec, exec, s[18:19]
	s_waitcnt vmcnt(0) lgkmcnt(0)
	s_barrier
	v_lshl_add_u32 v8, v60, 2, s45
	s_add_i32 s4, s45, s6
	s_ashr_i32 s18, s26, 6
	ds_read_b32 v28, v8
	v_lshl_add_u32 v8, v59, 2, s4
	s_lshl_b32 s4, s26, 6
	s_mulk_i32 s26, 0xfd00
	s_ashr_i32 s19, s18, 31
	s_add_i32 s52, s33, s26
	s_lshl_b64 s[18:19], s[18:19], 12
	s_and_b32 s4, s4, 0xfc0
	s_ashr_i32 s53, s52, 31
	ds_read2st64_b32 v[30:31], v8 offset0:1 offset1:2
	v_lshl_add_u32 v8, v71, 2, s45
	s_or_b32 s4, s18, s4
	s_mov_b64 s[50:51], s[24:25]
	s_lshl_b64 s[54:55], s[52:53], 2
	ds_read_b32 v46, v8
	v_or_b32_e32 v24, s4, v60
	s_add_u32 s4, s50, s54
	s_addc_u32 s5, s51, s55
	s_lshl_b32 s18, s12, 2
	s_add_u32 s50, s4, s18
	s_addc_u32 s51, s5, 0
	v_lshlrev_b32_e32 v50, 2, v62
	s_waitcnt lgkmcnt(3)
	v_mov_b64_e32 v[8:9], s[20:21]
	v_lshl_add_u64 v[26:27], s[50:51], 0, v[50:51]
	v_mad_u64_u32 v[8:9], s[50:51], v24, s13, v[8:9]
	v_mad_i32_i24 v9, s19, v127, v9
	s_lshl_b64 s[50:51], s[52:53], 1
	v_lshl_add_u64 v[8:9], v[8:9], 0, s[50:51]
	s_lshl_b32 s26, s12, 1
	v_lshl_add_u64 v[8:9], v[8:9], 0, s[26:27]
	v_lshlrev_b32_e32 v50, 1, v62
	v_lshl_add_u64 v[36:37], v[8:9], 0, v[50:51]
	s_nop 0
	s_nop 0
	s_nop 0
	s_nop 0
	s_nop 0
	s_nop 0
	v_mov_b32_e32 v25, s19
	v_lshlrev_b64 v[44:45], 11, v[24:25]
	s_nop 0
	s_nop 0
	s_nop 0
	s_waitcnt lgkmcnt(0)
	v_mov_b32_e32 v29, v31
	v_mov_b32_e32 v31, v46
	v_pk_add_f32 v[28:29], v[28:29], v[30:31]
	s_mov_b32 s4, 0xf800000
	v_add_f32_e32 v28, v28, v29
	v_fmamk_f32 v28, v28, 0x3c000000, v125
	v_mul_f32_e32 v29, 0x4f800000, v28
	v_cmp_gt_f32_e32 vcc, s4, v28
	s_add_i32 s49, s49, 1
	s_add_i32 s33, s33, s40
	v_cndmask_b32_e32 v30, v28, v29, vcc
	v_sqrt_f32_e32 v31, v30
	v_lshl_add_u64 v[28:29], s[22:23], 0, v[44:45]
	v_lshl_add_u64 v[28:29], v[28:29], 0, s[50:51]
	v_lshl_add_u64 v[28:29], v[28:29], 0, s[26:27]
	v_add_u32_e32 v44, -1, v31
	v_add_u32_e32 v45, 1, v31
	v_fma_f32 v46, -v44, v31, v30
	v_fma_f32 v47, -v45, v31, v30
	v_cmp_ge_f32_e64 s[18:19], 0, v46
	v_lshl_add_u64 v[28:29], v[28:29], 0, v[50:51]
	v_lshl_add_u64 v[28:29], v[28:29], 0, v[50:51]
	s_add_i32 s41, s41, s48
	v_cndmask_b32_e64 v31, v31, v44, s[18:19]
	v_cmp_lt_f32_e64 s[18:19], 0, v47
	s_nop 1
	v_cndmask_b32_e64 v31, v31, v45, s[18:19]
	v_mul_f32_e32 v44, 0x37800000, v31
	v_cndmask_b32_e32 v31, v31, v44, vcc
	v_cmp_class_f32_e32 vcc, v30, v126
	s_nop 1
	v_cndmask_b32_e32 v30, v31, v30, vcc
	v_div_scale_f32 v31, s[18:19], v30, v30, 1.0
	v_rcp_f32_e32 v44, v31
	v_div_scale_f32 v45, vcc, 1.0, v30, 1.0
	s_mov_b32 s19, s44
	v_fma_f32 v46, -v31, v44, 1.0
	v_fmac_f32_e32 v44, v46, v44
	v_mul_f32_e32 v46, v45, v44
	v_fma_f32 v47, -v31, v46, v45
	v_fmac_f32_e32 v46, v47, v44
	v_fma_f32 v31, -v31, v46, v45
	v_div_fmas_f32 v31, v31, v44, v46
	v_div_fixup_f32 v30, v31, v30, 1.0
	v_pk_mul_f32 v[34:35], v[34:35], v[30:31] op_sel_hi:[1,0]
	v_pk_mul_f32 v[32:33], v[32:33], v[30:31] op_sel_hi:[1,0]
	v_pk_mul_f32 v[6:7], v[6:7], v[30:31] op_sel_hi:[1,0]
	v_pk_mul_f32 v[4:5], v[4:5], v[30:31] op_sel_hi:[1,0]
	v_pk_mul_f32 v[2:3], v[2:3], v[30:31] op_sel_hi:[1,0]
	v_pk_mul_f32 v[0:1], v[0:1], v[30:31] op_sel_hi:[1,0]
	s_andn2_b64 vcc, exec, s[46:47]
	s_waitcnt vmcnt(0)
	v_pk_mul_f32 v[8:9], v[160:161], v[34:35]
	v_lshlrev_b32_e32 v34, 16, v176
	v_and_b32_e32 v35, 0xffff0000, v176
	v_pk_mul_f32 v[10:11], v[162:163], v[32:33]
	v_lshlrev_b32_e32 v32, 16, v177
	v_and_b32_e32 v33, 0xffff0000, v177
	v_pk_mul_f32 v[8:9], v[8:9], v[34:35]
	v_pk_mul_f32 v[10:11], v[10:11], v[32:33]
	v_cvt_pk_bf16_f32 v8, v8, v9
	v_cvt_pk_bf16_f32 v9, v10, v11
	v_pk_mul_f32 v[184:185], v[18:19], v[30:31] op_sel_hi:[1,0]
	v_lshlrev_b32_e32 v186, 16, v178
	v_pk_mul_f32 v[184:185], v[164:165], v[184:185]
	v_and_b32_e32 v187, 0xffff0000, v178
	v_pk_mul_f32 v[184:185], v[184:185], v[186:187]
	v_pk_mul_f32 v[186:187], v[16:17], v[30:31] op_sel_hi:[1,0]
	v_lshlrev_b32_e32 v188, 16, v179
	v_pk_mul_f32 v[186:187], v[166:167], v[186:187]
	v_and_b32_e32 v189, 0xffff0000, v179
	v_pk_mul_f32 v[186:187], v[186:187], v[188:189]
	v_cvt_pk_bf16_f32 v10, v184, v185
	v_cvt_pk_bf16_f32 v11, v186, v187
	s_nop 1
	v_permlane32_swap_b32_e32 v8, v10
	v_permlane32_swap_b32_e32 v9, v11
	global_store_dwordx4 v[28:29], v[8:11], off
	s_nop 1
	v_pk_mul_f32 v[6:7], v[6:7], v[168:169]
	v_lshlrev_b32_e32 v8, 16, v180
	v_and_b32_e32 v9, 0xffff0000, v180
	v_pk_mul_f32 v[6:7], v[6:7], v[8:9]
	v_pk_mul_f32 v[4:5], v[4:5], v[170:171]
	v_lshlrev_b32_e32 v8, 16, v181
	v_and_b32_e32 v9, 0xffff0000, v181
	v_pk_mul_f32 v[4:5], v[4:5], v[8:9]
	v_cvt_pk_bf16_f32 v6, v6, v7
	v_cvt_pk_bf16_f32 v7, v4, v5
	v_pk_mul_f32 v[2:3], v[2:3], v[172:173]
	v_lshlrev_b32_e32 v4, 16, v182
	v_and_b32_e32 v5, 0xffff0000, v182
	v_pk_mul_f32 v[2:3], v[2:3], v[4:5]
	v_pk_mul_f32 v[0:1], v[0:1], v[174:175]
	v_lshlrev_b32_e32 v4, 16, v183
	v_and_b32_e32 v5, 0xffff0000, v183
	v_pk_mul_f32 v[0:1], v[0:1], v[4:5]
	v_cvt_pk_bf16_f32 v2, v2, v3
	v_cvt_pk_bf16_f32 v3, v0, v1
	v_mov_b32_e32 v4, v6
	v_mov_b32_e32 v5, v7
	v_mov_b32_e32 v6, v2
	v_mov_b32_e32 v7, v3
	s_nop 1
	v_permlane32_swap_b32_e32 v4, v6
	v_permlane32_swap_b32_e32 v5, v7
	global_store_dwordx4 v[28:29], v[4:7], off offset:32
	s_nop 1
	s_cbranch_vccz .LBB0_1433
